# bundle: attention packed split + value-shuffle cleanup, and the first K iteration of the P1/P3a GEMM tiles peeled (zero C operand, no accumulator zeroing pass, first two phase waits leave the epilogue
# speedup vs baseline: 1.0078x; 1.0078x over previous
.LBB0_165:
	v_readlane_b32 s46, v253, 18
	v_readlane_b32 s47, v253, 19
	v_mov_b32_e32 v131, v1
	v_readlane_b32 s44, v253, 14
	v_lshl_add_u64 v[10:11], s[46:47], 0, v[0:1]
	v_lshl_add_u64 v[12:13], s[46:47], 0, v[130:131]
	v_mov_b32_e32 v135, v1
	v_readlane_b32 s45, v253, 15
	s_add_i32 m0, s52, 0x18000
	v_lshl_add_u64 v[10:11], v[10:11], 0, s[54:55]
	v_lshl_add_u64 v[14:15], s[44:45], 0, v[134:135]
	v_mov_b32_e32 v133, v1
	s_waitcnt vmcnt(2)
	s_barrier
	global_load_lds_dwordx4 v[10:11], off
	v_lshl_add_u64 v[10:11], v[12:13], 0, s[54:55]
	s_add_i32 m0, s52, 0x1a000
	s_add_i32 s61, s52, 0x8000
	v_lshl_add_u64 v[16:17], s[44:45], 0, v[132:133]
	global_load_lds_dwordx4 v[10:11], off
	v_lshl_add_u64 v[10:11], v[14:15], 0, s[54:55]
	s_mov_b32 m0, s61
	s_add_i32 s62, s52, 0xa000
	v_readlane_b32 s6, v253, 20
	global_load_lds_dwordx4 v[10:11], off
	v_lshl_add_u64 v[10:11], v[16:17], 0, s[54:55]
	s_mov_b32 m0, s62
	v_readlane_b32 s7, v253, 21
	global_load_lds_dwordx4 v[10:11], off
	s_add_i32 m0, s52, 0x1c000
	v_lshl_add_u64 v[10:11], s[6:7], 0, v[0:1]
	global_load_lds_dwordx4 v[10:11], off
	v_lshl_add_u64 v[10:11], s[6:7], 0, v[130:131]
	s_add_i32 m0, s52, 0x1e000
	s_and_b32 s5, s3, 3
	global_load_lds_dwordx4 v[10:11], off
	v_and_b32_e32 v10, 15, v3
	v_bfe_u32 v11, v3, 4, 2
	v_lshl_or_b32 v170, s4, 6, v10
	v_lshlrev_b32_e32 v12, 3, v11
	v_lshlrev_b32_e32 v11, 4, v11
	v_lshl_or_b32 v10, v10, 6, v11
	v_lshlrev_b32_e32 v11, 2, v170
	s_lshl_b32 s4, s4, 13
	v_and_b32_e32 v13, 32, v11
	v_lshrrev_b32_e32 v9, 4, v3
	v_bitop3_b32 v13, v10, s4, v13 bitop3:0xde
	s_lshl_b32 s4, s5, 12
	v_lshlrev_b32_e32 v3, 2, v3
	v_and_b32_e32 v3, 32, v3
	s_cmp_gt_i32 s50, 0
	v_bitop3_b32 v171, v10, s4, v3 bitop3:0xde
	s_cselect_b64 s[6:7], -1, 0
	s_add_i32 s64, s50, -2
	v_bitop3_b32 v3, s3, v9, 3 bitop3:0xa8
	s_cmpk_lt_u32 s2, 0x100
	v_cmp_eq_u32_e64 s[2:3], 0, v3
	v_lshlrev_b32_e32 v3, 14, v7
	v_and_b32_e32 v3, 0xffff8000, v3
	v_lshl_add_u32 v3, v6, 11, v3
	v_and_b32_e32 v6, 1, v7
	v_lshl_or_b32 v3, v6, 6, v3
	v_lshl_add_u32 v136, v8, 1, v3
	v_lshlrev_b32_e32 v3, 14, v2
	v_and_b32_e32 v3, 0xffff8000, v3
	s_waitcnt vmcnt(6)
	v_readlane_b32 s4, v254, 30
	v_lshl_add_u32 v3, v4, 11, v3
	v_and_b32_e32 v2, 1, v2
	v_lshl_or_b32 v172, s5, 5, v12
	v_add_u32_e32 v173, s4, v11
	v_lshl_or_b32 v2, v2, 6, v3
	v_readlane_b32 s4, v253, 10
	s_mov_b32 s63, 0
	s_cselect_b64 s[8:9], -1, 0
	v_mov_b32_e32 v137, v1
	v_lshl_add_u32 v138, v5, 1, v2
	v_mov_b32_e32 v139, v1
	v_add_u32_e32 v174, 0, v13
	v_readlane_b32 s65, v253, 9
	s_mov_b32 s66, s4
	s_barrier
	v_readlane_b32 s5, v253, 11
	s_waitcnt vmcnt(0)
	s_branch .LBB0_168

.LBB0_174:
	s_ashr_i32 s13, s12, 31
	s_lshl_b64 s[40:41], s[12:13], 19
	s_add_u32 s40, s30, s40
	s_addc_u32 s41, s31, s41
	s_ashr_i32 s11, s10, 31
	s_lshl_b64 s[42:43], s[10:11], 19
	v_readlane_b32 s48, v251, 29
	v_readlane_b32 s49, v251, 30
	s_add_u32 s42, s48, s42
	s_addc_u32 s43, s49, s43
	s_andn2_b64 vcc, exec, s[6:7]
	s_cbranch_vccnz .LBB0_188
	s_and_b64 s[48:49], s[4:5], exec
	s_cselect_b32 s11, s41, s45
	s_cselect_b32 s13, s40, s44
	s_cselect_b32 s67, s43, s47
	s_cselect_b32 s76, s42, s46
	s_add_u32 s44, s44, 0x40080
	s_addc_u32 s45, s45, 0
	s_add_u32 s77, s46, 0x100
	s_addc_u32 s78, s47, 0
	s_mov_b32 s46, 0
	s_add_i32 s79, s46, 2
	s_add_u32 s47, s44, 0xfffc0080
	s_addc_u32 s48, s45, -1
	s_add_i32 s80, 0, 0x10000
	s_cmp_eq_u32 s64, s46
	s_cselect_b32 s49, s11, s48
	s_cselect_b32 s48, s13, s47
	s_waitcnt lgkmcnt(0)
	v_add_u32_e32 v144, s80, v171
	s_cselect_b32 s47, s67, s78
	s_cselect_b32 s46, s76, s77
	s_add_i32 s82, 0, 0x14000
	ds_read_b128 v[140:143], v144
	ds_read_b128 v[162:165], v144 offset:1024
	ds_read_b128 v[166:169], v144 offset:2048
	ds_read_b128 v[176:179], v144 offset:3072
	v_add_u32_e32 v144, s82, v171
	ds_read_b128 v[180:183], v144
	ds_read_b128 v[184:187], v144 offset:1024
	ds_read_b128 v[188:191], v144 offset:2048
	ds_read_b128 v[192:195], v144 offset:3072
	v_lshl_add_u64 v[144:145], s[44:45], 0, v[136:137]
	s_add_i32 m0, s52, 0xc000
	ds_read_b128 v[212:215], v174
	ds_read_b128 v[216:219], v174 offset:1024
	ds_read_b128 v[220:223], v174 offset:2048
	ds_read_b128 v[224:227], v174 offset:3072
	ds_read_b128 v[228:231], v174 offset:4096
	ds_read_b128 v[232:235], v174 offset:5120
	ds_read_b128 v[236:239], v174 offset:6144
	ds_read_b128 v[240:243], v174 offset:7168
	global_load_lds_dwordx4 v[144:145], off
	v_lshl_add_u64 v[144:145], s[44:45], 0, v[138:139]
	s_add_i32 m0, s52, 0xe000
	s_nop 0
	global_load_lds_dwordx4 v[144:145], off
	s_waitcnt vmcnt(24)
	s_waitcnt lgkmcnt(0)
	s_barrier
	s_setprio 1
	s_waitcnt lgkmcnt(0)
	v_mfma_f32_16x16x32_bf16 v[126:129], v[140:143], v[212:215], 0
	v_mfma_f32_16x16x32_bf16 v[122:125], v[166:169], v[212:215], 0
	v_mfma_f32_16x16x32_bf16 v[110:113], v[140:143], v[220:223], 0
	v_mfma_f32_16x16x32_bf16 v[106:109], v[166:169], v[220:223], 0
	v_mfma_f32_16x16x32_bf16 v[94:97], v[140:143], v[228:231], 0
	v_mfma_f32_16x16x32_bf16 v[90:93], v[166:169], v[228:231], 0
	v_mfma_f32_16x16x32_bf16 v[78:81], v[140:143], v[236:239], 0
	v_mfma_f32_16x16x32_bf16 v[74:77], v[166:169], v[236:239], 0
	v_mfma_f32_16x16x32_bf16 v[126:129], v[162:165], v[216:219], v[126:129]
	v_mfma_f32_16x16x32_bf16 v[122:125], v[176:179], v[216:219], v[122:125]
	v_mfma_f32_16x16x32_bf16 v[110:113], v[162:165], v[224:227], v[110:113]
	v_mfma_f32_16x16x32_bf16 v[106:109], v[176:179], v[224:227], v[106:109]
	v_mfma_f32_16x16x32_bf16 v[94:97], v[162:165], v[232:235], v[94:97]
	v_mfma_f32_16x16x32_bf16 v[90:93], v[176:179], v[232:235], v[90:93]
	v_mfma_f32_16x16x32_bf16 v[78:81], v[162:165], v[240:243], v[78:81]
	v_mfma_f32_16x16x32_bf16 v[74:77], v[176:179], v[240:243], v[74:77]
	s_setprio 0
	s_setprio 1
	v_mfma_f32_16x16x32_bf16 v[118:121], v[180:183], v[212:215], 0
	v_mfma_f32_16x16x32_bf16 v[114:117], v[188:191], v[212:215], 0
	v_mfma_f32_16x16x32_bf16 v[102:105], v[180:183], v[220:223], 0
	v_mfma_f32_16x16x32_bf16 v[98:101], v[188:191], v[220:223], 0
	v_mfma_f32_16x16x32_bf16 v[86:89], v[180:183], v[228:231], 0
	v_mfma_f32_16x16x32_bf16 v[82:85], v[188:191], v[228:231], 0
	v_mfma_f32_16x16x32_bf16 v[70:73], v[180:183], v[236:239], 0
	v_mfma_f32_16x16x32_bf16 v[66:69], v[188:191], v[236:239], 0
	v_mfma_f32_16x16x32_bf16 v[118:121], v[184:187], v[216:219], v[118:121]
	v_mfma_f32_16x16x32_bf16 v[114:117], v[192:195], v[216:219], v[114:117]
	v_mfma_f32_16x16x32_bf16 v[102:105], v[184:187], v[224:227], v[102:105]
	v_mfma_f32_16x16x32_bf16 v[98:101], v[192:195], v[224:227], v[98:101]
	v_mfma_f32_16x16x32_bf16 v[86:89], v[184:187], v[232:235], v[86:89]
	v_mfma_f32_16x16x32_bf16 v[82:85], v[192:195], v[232:235], v[82:85]
	v_mfma_f32_16x16x32_bf16 v[70:73], v[184:187], v[240:243], v[70:73]
	v_mfma_f32_16x16x32_bf16 v[66:69], v[192:195], v[240:243], v[66:69]
	s_setprio 0
	s_barrier
	s_add_i32 s80, s80, s51
	v_lshl_add_u64 v[144:145], s[46:47], 0, v[0:1]
	s_mov_b32 m0, s80
	ds_read_b128 v[212:215], v174 offset:16384
	ds_read_b128 v[216:219], v174 offset:17408
	ds_read_b128 v[220:223], v174 offset:18432
	ds_read_b128 v[224:227], v174 offset:19456
	ds_read_b128 v[228:231], v174 offset:20480
	ds_read_b128 v[232:235], v174 offset:21504
	ds_read_b128 v[236:239], v174 offset:22528
	ds_read_b128 v[240:243], v174 offset:23552
	global_load_lds_dwordx4 v[144:145], off
	s_add_i32 m0, s80, 0x2000
	s_add_u32 s80, s46, 0x40000
	v_lshl_add_u64 v[244:245], s[46:47], 0, v[130:131]
	s_addc_u32 s81, s47, 0
	s_add_i32 s82, s82, s51
	global_load_lds_dwordx4 v[244:245], off
	v_lshl_add_u64 v[246:247], s[80:81], 0, v[0:1]
	s_mov_b32 m0, s82
	v_lshl_add_u64 v[248:249], s[48:49], 0, v[132:133]
	global_load_lds_dwordx4 v[246:247], off
	v_lshl_add_u64 v[246:247], s[80:81], 0, v[130:131]
	s_add_i32 m0, s82, 0x2000
	s_nop 0
	global_load_lds_dwordx4 v[246:247], off
	v_lshl_add_u64 v[246:247], s[48:49], 0, v[134:135]
	s_mov_b32 m0, s52
	s_nop 0
	global_load_lds_dwordx4 v[246:247], off
	s_mov_b32 m0, s58
	s_nop 0
	global_load_lds_dwordx4 v[248:249], off
	s_waitcnt vmcnt(24)
	s_waitcnt lgkmcnt(0)
	s_barrier
	s_setprio 1
	s_waitcnt lgkmcnt(0)
	v_mfma_f32_16x16x32_bf16 v[62:65], v[140:143], v[212:215], 0
	v_mfma_f32_16x16x32_bf16 v[58:61], v[166:169], v[212:215], 0
	v_mfma_f32_16x16x32_bf16 v[46:49], v[140:143], v[220:223], 0
	v_mfma_f32_16x16x32_bf16 v[42:45], v[166:169], v[220:223], 0
	v_mfma_f32_16x16x32_bf16 v[30:33], v[140:143], v[228:231], 0
	v_mfma_f32_16x16x32_bf16 v[26:29], v[166:169], v[228:231], 0
	v_mfma_f32_16x16x32_bf16 v[14:17], v[140:143], v[236:239], 0
	v_mfma_f32_16x16x32_bf16 v[10:13], v[166:169], v[236:239], 0
	v_mfma_f32_16x16x32_bf16 v[62:65], v[162:165], v[216:219], v[62:65]
	v_mfma_f32_16x16x32_bf16 v[58:61], v[176:179], v[216:219], v[58:61]
	v_mfma_f32_16x16x32_bf16 v[46:49], v[162:165], v[224:227], v[46:49]
	v_mfma_f32_16x16x32_bf16 v[42:45], v[176:179], v[224:227], v[42:45]
	v_mfma_f32_16x16x32_bf16 v[30:33], v[162:165], v[232:235], v[30:33]
	v_mfma_f32_16x16x32_bf16 v[26:29], v[176:179], v[232:235], v[26:29]
	v_mfma_f32_16x16x32_bf16 v[14:17], v[162:165], v[240:243], v[14:17]
	v_mfma_f32_16x16x32_bf16 v[10:13], v[176:179], v[240:243], v[10:13]
	s_setprio 0
	s_setprio 1
	v_mfma_f32_16x16x32_bf16 v[54:57], v[180:183], v[212:215], 0
	v_mfma_f32_16x16x32_bf16 v[50:53], v[188:191], v[212:215], 0
	v_mfma_f32_16x16x32_bf16 v[38:41], v[180:183], v[220:223], 0
	v_mfma_f32_16x16x32_bf16 v[34:37], v[188:191], v[220:223], 0
	v_mfma_f32_16x16x32_bf16 v[22:25], v[180:183], v[228:231], 0
	v_mfma_f32_16x16x32_bf16 v[18:21], v[188:191], v[228:231], 0
	v_mfma_f32_16x16x32_bf16 v[6:9], v[180:183], v[236:239], 0
	v_mfma_f32_16x16x32_bf16 v[2:5], v[188:191], v[236:239], 0
	v_mfma_f32_16x16x32_bf16 v[54:57], v[184:187], v[216:219], v[54:57]
	v_mfma_f32_16x16x32_bf16 v[50:53], v[192:195], v[216:219], v[50:53]
	v_mfma_f32_16x16x32_bf16 v[38:41], v[184:187], v[224:227], v[38:41]
	v_mfma_f32_16x16x32_bf16 v[34:37], v[192:195], v[224:227], v[34:37]
	v_mfma_f32_16x16x32_bf16 v[22:25], v[184:187], v[232:235], v[22:25]
	v_mfma_f32_16x16x32_bf16 v[18:21], v[192:195], v[232:235], v[18:21]
	v_mfma_f32_16x16x32_bf16 v[6:9], v[184:187], v[240:243], v[6:9]
	v_mfma_f32_16x16x32_bf16 v[2:5], v[192:195], v[240:243], v[2:5]
	s_setprio 0
	s_barrier
	s_add_i32 s80, 0, 0x18000
	v_add_u32_e32 v148, s80, v171
	s_add_i32 s81, 0, 0x1c000
	ds_read_b128 v[140:143], v148
	ds_read_b128 v[162:165], v148 offset:1024
	ds_read_b128 v[166:169], v148 offset:2048
	ds_read_b128 v[176:179], v148 offset:3072
	v_add_u32_e32 v148, s81, v171
	ds_read_b128 v[180:183], v148
	ds_read_b128 v[184:187], v148 offset:1024
	ds_read_b128 v[188:191], v148 offset:2048
	ds_read_b128 v[192:195], v148 offset:3072
	s_add_u32 s48, s48, 0x40000
	s_addc_u32 s49, s49, 0
	s_mov_b32 m0, s59
	v_lshl_add_u64 v[148:149], s[48:49], 0, v[134:135]
	ds_read_b128 v[212:215], v174 offset:32768
	ds_read_b128 v[216:219], v174 offset:33792
	ds_read_b128 v[220:223], v174 offset:34816
	ds_read_b128 v[224:227], v174 offset:35840
	ds_read_b128 v[228:231], v174 offset:36864
	ds_read_b128 v[232:235], v174 offset:37888
	ds_read_b128 v[236:239], v174 offset:38912
	ds_read_b128 v[240:243], v174 offset:39936
	global_load_lds_dwordx4 v[148:149], off
	v_lshl_add_u64 v[148:149], s[48:49], 0, v[132:133]
	s_mov_b32 m0, s60
	s_nop 0
	global_load_lds_dwordx4 v[148:149], off
	s_waitcnt vmcnt(8)
	s_waitcnt lgkmcnt(0)
	s_barrier
	s_setprio 1
	s_waitcnt lgkmcnt(0)
	v_mfma_f32_16x16x32_bf16 v[126:129], v[140:143], v[212:215], v[126:129]
	v_mfma_f32_16x16x32_bf16 v[122:125], v[166:169], v[212:215], v[122:125]
	v_mfma_f32_16x16x32_bf16 v[110:113], v[140:143], v[220:223], v[110:113]
	v_mfma_f32_16x16x32_bf16 v[106:109], v[166:169], v[220:223], v[106:109]
	v_mfma_f32_16x16x32_bf16 v[94:97], v[140:143], v[228:231], v[94:97]
	v_mfma_f32_16x16x32_bf16 v[90:93], v[166:169], v[228:231], v[90:93]
	v_mfma_f32_16x16x32_bf16 v[78:81], v[140:143], v[236:239], v[78:81]
	v_mfma_f32_16x16x32_bf16 v[74:77], v[166:169], v[236:239], v[74:77]
	v_mfma_f32_16x16x32_bf16 v[126:129], v[162:165], v[216:219], v[126:129]
	v_mfma_f32_16x16x32_bf16 v[122:125], v[176:179], v[216:219], v[122:125]
	v_mfma_f32_16x16x32_bf16 v[110:113], v[162:165], v[224:227], v[110:113]
	v_mfma_f32_16x16x32_bf16 v[106:109], v[176:179], v[224:227], v[106:109]
	v_mfma_f32_16x16x32_bf16 v[94:97], v[162:165], v[232:235], v[94:97]
	v_mfma_f32_16x16x32_bf16 v[90:93], v[176:179], v[232:235], v[90:93]
	v_mfma_f32_16x16x32_bf16 v[78:81], v[162:165], v[240:243], v[78:81]
	v_mfma_f32_16x16x32_bf16 v[74:77], v[176:179], v[240:243], v[74:77]
	s_setprio 0
	s_setprio 1
	v_mfma_f32_16x16x32_bf16 v[118:121], v[180:183], v[212:215], v[118:121]
	v_mfma_f32_16x16x32_bf16 v[114:117], v[188:191], v[212:215], v[114:117]
	v_mfma_f32_16x16x32_bf16 v[102:105], v[180:183], v[220:223], v[102:105]
	v_mfma_f32_16x16x32_bf16 v[98:101], v[188:191], v[220:223], v[98:101]
	v_mfma_f32_16x16x32_bf16 v[86:89], v[180:183], v[228:231], v[86:89]
	v_mfma_f32_16x16x32_bf16 v[82:85], v[188:191], v[228:231], v[82:85]
	v_mfma_f32_16x16x32_bf16 v[70:73], v[180:183], v[236:239], v[70:73]
	v_mfma_f32_16x16x32_bf16 v[66:69], v[188:191], v[236:239], v[66:69]
	v_mfma_f32_16x16x32_bf16 v[118:121], v[184:187], v[216:219], v[118:121]
	v_mfma_f32_16x16x32_bf16 v[114:117], v[192:195], v[216:219], v[114:117]
	v_mfma_f32_16x16x32_bf16 v[102:105], v[184:187], v[224:227], v[102:105]
	v_mfma_f32_16x16x32_bf16 v[98:101], v[192:195], v[224:227], v[98:101]
	v_mfma_f32_16x16x32_bf16 v[86:89], v[184:187], v[232:235], v[86:89]
	v_mfma_f32_16x16x32_bf16 v[82:85], v[192:195], v[232:235], v[82:85]
	v_mfma_f32_16x16x32_bf16 v[70:73], v[184:187], v[240:243], v[70:73]
	v_mfma_f32_16x16x32_bf16 v[66:69], v[192:195], v[240:243], v[66:69]
	s_setprio 0
	s_barrier
	s_add_i32 s48, s80, s51
	v_lshl_add_u64 v[144:145], v[144:145], 0, s[54:55]
	s_mov_b32 m0, s48
	ds_read_b128 v[212:215], v174 offset:49152
	ds_read_b128 v[216:219], v174 offset:50176
	ds_read_b128 v[220:223], v174 offset:51200
	ds_read_b128 v[224:227], v174 offset:52224
	ds_read_b128 v[228:231], v174 offset:53248
	ds_read_b128 v[232:235], v174 offset:54272
	ds_read_b128 v[236:239], v174 offset:55296
	ds_read_b128 v[240:243], v174 offset:56320
	global_load_lds_dwordx4 v[144:145], off
	s_add_i32 m0, s48, 0x2000
	s_add_u32 s46, s46, 0x40080
	v_lshl_add_u64 v[144:145], v[244:245], 0, s[54:55]
	s_addc_u32 s47, s47, 0
	s_add_i32 s48, s81, s51
	global_load_lds_dwordx4 v[144:145], off
	v_lshl_add_u64 v[144:145], s[46:47], 0, v[0:1]
	s_mov_b32 m0, s48
	s_nop 0
	global_load_lds_dwordx4 v[144:145], off
	v_lshl_add_u64 v[144:145], s[46:47], 0, v[130:131]
	s_add_i32 m0, s48, 0x2000
	s_nop 0
	global_load_lds_dwordx4 v[144:145], off
	v_lshl_add_u64 v[144:145], v[246:247], 0, s[54:55]
	s_mov_b32 m0, s61
	s_nop 0
	global_load_lds_dwordx4 v[144:145], off
	v_lshl_add_u64 v[144:145], v[248:249], 0, s[54:55]
	s_mov_b32 m0, s62
	s_nop 0
	global_load_lds_dwordx4 v[144:145], off
	s_waitcnt vmcnt(8)
	s_waitcnt lgkmcnt(0)
	s_barrier
	s_setprio 1
	s_waitcnt lgkmcnt(0)
	v_mfma_f32_16x16x32_bf16 v[62:65], v[140:143], v[212:215], v[62:65]
	v_mfma_f32_16x16x32_bf16 v[58:61], v[166:169], v[212:215], v[58:61]
	v_mfma_f32_16x16x32_bf16 v[46:49], v[140:143], v[220:223], v[46:49]
	v_mfma_f32_16x16x32_bf16 v[42:45], v[166:169], v[220:223], v[42:45]
	v_mfma_f32_16x16x32_bf16 v[30:33], v[140:143], v[228:231], v[30:33]
	v_mfma_f32_16x16x32_bf16 v[26:29], v[166:169], v[228:231], v[26:29]
	v_mfma_f32_16x16x32_bf16 v[14:17], v[140:143], v[236:239], v[14:17]
	v_mfma_f32_16x16x32_bf16 v[10:13], v[166:169], v[236:239], v[10:13]
	v_mfma_f32_16x16x32_bf16 v[62:65], v[162:165], v[216:219], v[62:65]
	v_mfma_f32_16x16x32_bf16 v[58:61], v[176:179], v[216:219], v[58:61]
	v_mfma_f32_16x16x32_bf16 v[46:49], v[162:165], v[224:227], v[46:49]
	v_mfma_f32_16x16x32_bf16 v[42:45], v[176:179], v[224:227], v[42:45]
	v_mfma_f32_16x16x32_bf16 v[30:33], v[162:165], v[232:235], v[30:33]
	v_mfma_f32_16x16x32_bf16 v[26:29], v[176:179], v[232:235], v[26:29]
	v_mfma_f32_16x16x32_bf16 v[14:17], v[162:165], v[240:243], v[14:17]
	v_mfma_f32_16x16x32_bf16 v[10:13], v[176:179], v[240:243], v[10:13]
	s_setprio 0
	s_setprio 1
	v_mfma_f32_16x16x32_bf16 v[54:57], v[180:183], v[212:215], v[54:57]
	v_mfma_f32_16x16x32_bf16 v[50:53], v[188:191], v[212:215], v[50:53]
	v_mfma_f32_16x16x32_bf16 v[38:41], v[180:183], v[220:223], v[38:41]
	v_mfma_f32_16x16x32_bf16 v[34:37], v[188:191], v[220:223], v[34:37]
	v_mfma_f32_16x16x32_bf16 v[22:25], v[180:183], v[228:231], v[22:25]
	v_mfma_f32_16x16x32_bf16 v[18:21], v[188:191], v[228:231], v[18:21]
	v_mfma_f32_16x16x32_bf16 v[6:9], v[180:183], v[236:239], v[6:9]
	v_mfma_f32_16x16x32_bf16 v[2:5], v[188:191], v[236:239], v[2:5]
	v_mfma_f32_16x16x32_bf16 v[54:57], v[184:187], v[216:219], v[54:57]
	v_mfma_f32_16x16x32_bf16 v[50:53], v[192:195], v[216:219], v[50:53]
	v_mfma_f32_16x16x32_bf16 v[38:41], v[184:187], v[224:227], v[38:41]
	v_mfma_f32_16x16x32_bf16 v[34:37], v[192:195], v[224:227], v[34:37]
	v_mfma_f32_16x16x32_bf16 v[22:25], v[184:187], v[232:235], v[22:25]
	v_mfma_f32_16x16x32_bf16 v[18:21], v[192:195], v[232:235], v[18:21]
	v_mfma_f32_16x16x32_bf16 v[6:9], v[184:187], v[240:243], v[6:9]
	v_mfma_f32_16x16x32_bf16 v[2:5], v[192:195], v[240:243], v[2:5]
	s_setprio 0
	s_barrier
	s_add_u32 s44, s44, 0x100
	s_addc_u32 s45, s45, 0
	s_add_u32 s77, s77, 0x100
	s_addc_u32 s78, s78, 0
	s_cmp_ge_i32 s79, s50
	s_mov_b32 s46, s79
	s_cbranch_scc0 .LBB0_176
	s_branch .Lpeel_p1_after

.Lpeel_p1_after:
	s_and_b64 vcc, exec, s[8:9]
	s_cbranch_vccz .LBB0_179

.LBB0_182:
	s_or_b64 exec, exec, s[44:45]
	s_waitcnt vmcnt(0)
	s_cbranch_execz .LBB0_185

.LBB0_519:
	v_lshrrev_b32_e32 v18, 1, v12
	v_and_b32_e32 v13, 15, v12
	v_and_b32_e32 v18, 24, v18
	v_lshl_or_b32 v184, s4, 6, v13
	v_lshlrev_b32_e32 v19, 1, v18
	v_readlane_b32 s60, v253, 26
	v_lshl_or_b32 v13, v13, 6, v19
	v_lshlrev_b32_e32 v19, 2, v184
	s_lshl_b32 s3, s3, 5
	v_mov_b32_e32 v167, v1
	v_readlane_b32 s61, v253, 27
	s_lshl_b32 s4, s4, 13
	v_and_b32_e32 v20, 32, v19
	s_and_b32 s3, s3, 0x60
	v_lshlrev_b32_e32 v12, 2, v12
	v_lshl_add_u64 v[14:15], s[60:61], 0, v[166:167]
	v_mov_b32_e32 v163, v1
	v_bitop3_b32 v20, v13, s4, v20 bitop3:0xde
	s_lshl_b32 s4, s3, 7
	v_and_b32_e32 v12, 32, v12
	v_lshl_add_u64 v[16:17], s[60:61], 0, v[162:163]
	v_bitop3_b32 v185, v13, s4, v12 bitop3:0xde
	s_add_i32 m0, s51, 0x18000
	v_lshl_add_u64 v[12:13], v[14:15], 0, s[54:55]
	s_waitcnt vmcnt(2)
	s_barrier
	global_load_lds_dwordx4 v[12:13], off
	v_lshl_add_u64 v[12:13], v[16:17], 0, s[54:55]
	s_add_i32 m0, s51, 0x1a000
	s_add_i32 s79, s51, 0x8000
	global_load_lds_dwordx4 v[12:13], off
	v_lshl_add_u64 v[2:3], v[2:3], 0, s[54:55]
	s_mov_b32 m0, s79
	s_add_i32 s80, s51, 0xa000
	v_readlane_b32 s4, v253, 28
	global_load_lds_dwordx4 v[2:3], off
	v_lshl_add_u64 v[2:3], v[4:5], 0, s[54:55]
	s_mov_b32 m0, s80
	v_readlane_b32 s5, v253, 29
	global_load_lds_dwordx4 v[2:3], off
	s_add_i32 m0, s51, 0x1c000
	v_lshl_add_u64 v[2:3], s[4:5], 0, v[166:167]
	global_load_lds_dwordx4 v[2:3], off
	v_lshl_add_u64 v[2:3], s[4:5], 0, v[162:163]
	s_add_i32 m0, s51, 0x1e000
	s_cmp_gt_i32 s64, 0
	global_load_lds_dwordx4 v[2:3], off
	v_lshlrev_b32_e32 v2, 14, v10
	v_and_b32_e32 v2, 0xffff8000, v2
	v_lshl_add_u32 v2, v9, 11, v2
	v_and_b32_e32 v3, 1, v10
	v_lshl_or_b32 v2, v3, 6, v2
	v_lshl_add_u32 v168, v11, 1, v2
	v_lshlrev_b32_e32 v2, 14, v6
	v_and_b32_e32 v2, 0xffff8000, v2
	s_waitcnt vmcnt(6)
	s_cselect_b64 s[4:5], -1, 0
	s_add_i32 s82, s64, -2
	v_lshl_add_u32 v2, v7, 11, v2
	v_and_b32_e32 v3, 1, v6
	s_cmpk_lt_u32 s2, 0x100
	v_readlane_b32 s2, v254, 30
	v_lshl_or_b32 v2, v3, 6, v2
	s_mov_b32 s81, 0
	s_cselect_b64 s[40:41], -1, 0
	v_add_u32_e32 v186, s2, v19
	v_or_b32_e32 v187, s3, v18
	v_mov_b32_e32 v169, v1
	v_lshl_add_u32 v170, v8, 1, v2
	v_mov_b32_e32 v171, v1
	v_add_u32_e32 v188, 0, v20
	v_readlane_b32 s83, v253, 23
	s_barrier
	s_waitcnt vmcnt(0)
	s_branch .LBB0_522

.LBB0_528:
	s_ashr_i32 s45, s44, 31
	s_lshl_b64 s[46:47], s[44:45], 19
	s_add_u32 s46, s30, s46
	s_addc_u32 s47, s31, s47
	s_ashr_i32 s43, s42, 31
	s_lshl_b64 s[48:49], s[42:43], 19
	s_add_u32 s48, s68, s48
	s_addc_u32 s49, s69, s49
	s_andn2_b64 vcc, exec, s[4:5]
	s_cbranch_vccnz .LBB0_536
	s_and_b64 s[62:63], s[2:3], exec
	s_cselect_b32 s43, s47, s59
	s_cselect_b32 s45, s46, s58
	s_cselect_b32 s84, s49, s61
	s_cselect_b32 s85, s48, s60
	s_add_u32 s58, s58, 0x40080
	s_addc_u32 s59, s59, 0
	s_add_u32 s86, s60, 0x100
	s_addc_u32 s87, s61, 0
	s_mov_b32 s60, 0
	s_add_i32 s88, s60, 2
	s_add_u32 s61, s58, 0xfffc0080
	s_addc_u32 s62, s59, -1
	s_add_i32 s89, 0, 0x10000
	s_cmp_eq_u32 s82, s60
	s_cselect_b32 s63, s43, s62
	s_cselect_b32 s62, s45, s61
	s_cselect_b32 s61, s84, s87
	s_cselect_b32 s60, s85, s86
	s_add_i32 s92, 0, 0x14000
	v_add_u32_e32 v126, s89, v185
	v_add_u32_e32 v148, s92, v185
	ds_read_b128 v[114:117], v126
	ds_read_b128 v[118:121], v126 offset:1024
	ds_read_b128 v[122:125], v126 offset:2048
	ds_read_b128 v[126:129], v126 offset:3072
	ds_read_b128 v[172:175], v148
	ds_read_b128 v[176:179], v148 offset:1024
	ds_read_b128 v[180:183], v148 offset:2048
	ds_read_b128 v[190:193], v148 offset:3072
	v_lshl_add_u64 v[148:149], s[58:59], 0, v[168:169]
	s_add_i32 m0, s51, 0xc000
	ds_read_b128 v[212:215], v188
	ds_read_b128 v[216:219], v188 offset:1024
	ds_read_b128 v[220:223], v188 offset:2048
	ds_read_b128 v[224:227], v188 offset:3072
	ds_read_b128 v[228:231], v188 offset:4096
	ds_read_b128 v[232:235], v188 offset:5120
	ds_read_b128 v[236:239], v188 offset:6144
	ds_read_b128 v[240:243], v188 offset:7168
	global_load_lds_dwordx4 v[148:149], off
	v_lshl_add_u64 v[148:149], s[58:59], 0, v[170:171]
	s_add_i32 m0, s51, 0xe000
	s_nop 0
	global_load_lds_dwordx4 v[148:149], off
	s_waitcnt vmcnt(24)
	s_waitcnt lgkmcnt(0)
	s_barrier
	s_setprio 1
	s_waitcnt lgkmcnt(0)
	v_mfma_f32_16x16x32_bf16 v[142:145], v[114:117], v[212:215], 0
	v_mfma_f32_16x16x32_bf16 v[138:141], v[122:125], v[212:215], 0
	v_mfma_f32_16x16x32_bf16 v[110:113], v[114:117], v[220:223], 0
	v_mfma_f32_16x16x32_bf16 v[106:109], v[122:125], v[220:223], 0
	v_mfma_f32_16x16x32_bf16 v[94:97], v[114:117], v[228:231], 0
	v_mfma_f32_16x16x32_bf16 v[90:93], v[122:125], v[228:231], 0
	v_mfma_f32_16x16x32_bf16 v[78:81], v[114:117], v[236:239], 0
	v_mfma_f32_16x16x32_bf16 v[74:77], v[122:125], v[236:239], 0
	v_mfma_f32_16x16x32_bf16 v[142:145], v[118:121], v[216:219], v[142:145]
	v_mfma_f32_16x16x32_bf16 v[138:141], v[126:129], v[216:219], v[138:141]
	v_mfma_f32_16x16x32_bf16 v[110:113], v[118:121], v[224:227], v[110:113]
	v_mfma_f32_16x16x32_bf16 v[106:109], v[126:129], v[224:227], v[106:109]
	v_mfma_f32_16x16x32_bf16 v[94:97], v[118:121], v[232:235], v[94:97]
	v_mfma_f32_16x16x32_bf16 v[90:93], v[126:129], v[232:235], v[90:93]
	v_mfma_f32_16x16x32_bf16 v[78:81], v[118:121], v[240:243], v[78:81]
	v_mfma_f32_16x16x32_bf16 v[74:77], v[126:129], v[240:243], v[74:77]
	s_setprio 0
	s_setprio 1
	v_mfma_f32_16x16x32_bf16 v[134:137], v[172:175], v[212:215], 0
	v_mfma_f32_16x16x32_bf16 v[130:133], v[180:183], v[212:215], 0
	v_mfma_f32_16x16x32_bf16 v[102:105], v[172:175], v[220:223], 0
	v_mfma_f32_16x16x32_bf16 v[98:101], v[180:183], v[220:223], 0
	v_mfma_f32_16x16x32_bf16 v[86:89], v[172:175], v[228:231], 0
	v_mfma_f32_16x16x32_bf16 v[82:85], v[180:183], v[228:231], 0
	v_mfma_f32_16x16x32_bf16 v[70:73], v[172:175], v[236:239], 0
	v_mfma_f32_16x16x32_bf16 v[66:69], v[180:183], v[236:239], 0
	v_mfma_f32_16x16x32_bf16 v[134:137], v[176:179], v[216:219], v[134:137]
	v_mfma_f32_16x16x32_bf16 v[130:133], v[190:193], v[216:219], v[130:133]
	v_mfma_f32_16x16x32_bf16 v[102:105], v[176:179], v[224:227], v[102:105]
	v_mfma_f32_16x16x32_bf16 v[98:101], v[190:193], v[224:227], v[98:101]
	v_mfma_f32_16x16x32_bf16 v[86:89], v[176:179], v[232:235], v[86:89]
	v_mfma_f32_16x16x32_bf16 v[82:85], v[190:193], v[232:235], v[82:85]
	v_mfma_f32_16x16x32_bf16 v[70:73], v[176:179], v[240:243], v[70:73]
	v_mfma_f32_16x16x32_bf16 v[66:69], v[190:193], v[240:243], v[66:69]
	s_setprio 0
	s_barrier
	s_add_i32 s89, s89, s65
	v_lshl_add_u64 v[148:149], s[60:61], 0, v[166:167]
	s_mov_b32 m0, s89
	ds_read_b128 v[212:215], v188 offset:16384
	ds_read_b128 v[216:219], v188 offset:17408
	ds_read_b128 v[220:223], v188 offset:18432
	ds_read_b128 v[224:227], v188 offset:19456
	ds_read_b128 v[228:231], v188 offset:20480
	ds_read_b128 v[232:235], v188 offset:21504
	ds_read_b128 v[236:239], v188 offset:22528
	ds_read_b128 v[240:243], v188 offset:23552
	global_load_lds_dwordx4 v[148:149], off
	s_add_i32 m0, s89, 0x2000
	s_add_u32 s90, s60, 0x40000
	v_lshl_add_u64 v[194:195], s[60:61], 0, v[162:163]
	s_addc_u32 s91, s61, 0
	s_add_i32 s89, s92, s65
	global_load_lds_dwordx4 v[194:195], off
	v_lshl_add_u64 v[244:245], s[90:91], 0, v[166:167]
	s_mov_b32 m0, s89
	v_lshl_add_u64 v[246:247], s[62:63], 0, v[164:165]
	global_load_lds_dwordx4 v[244:245], off
	v_lshl_add_u64 v[244:245], s[90:91], 0, v[162:163]
	s_add_i32 m0, s89, 0x2000
	s_nop 0
	global_load_lds_dwordx4 v[244:245], off
	v_lshl_add_u64 v[244:245], s[62:63], 0, v[0:1]
	s_mov_b32 m0, s51
	s_nop 0
	global_load_lds_dwordx4 v[244:245], off
	s_mov_b32 m0, s76
	s_nop 0
	global_load_lds_dwordx4 v[246:247], off
	s_waitcnt vmcnt(24)
	s_waitcnt lgkmcnt(0)
	s_barrier
	s_setprio 1
	s_waitcnt lgkmcnt(0)
	v_mfma_f32_16x16x32_bf16 v[62:65], v[114:117], v[212:215], 0
	v_mfma_f32_16x16x32_bf16 v[58:61], v[122:125], v[212:215], 0
	v_mfma_f32_16x16x32_bf16 v[46:49], v[114:117], v[220:223], 0
	v_mfma_f32_16x16x32_bf16 v[42:45], v[122:125], v[220:223], 0
	v_mfma_f32_16x16x32_bf16 v[30:33], v[114:117], v[228:231], 0
	v_mfma_f32_16x16x32_bf16 v[26:29], v[122:125], v[228:231], 0
	v_mfma_f32_16x16x32_bf16 v[14:17], v[114:117], v[236:239], 0
	v_mfma_f32_16x16x32_bf16 v[10:13], v[122:125], v[236:239], 0
	v_mfma_f32_16x16x32_bf16 v[62:65], v[118:121], v[216:219], v[62:65]
	v_mfma_f32_16x16x32_bf16 v[58:61], v[126:129], v[216:219], v[58:61]
	v_mfma_f32_16x16x32_bf16 v[46:49], v[118:121], v[224:227], v[46:49]
	v_mfma_f32_16x16x32_bf16 v[42:45], v[126:129], v[224:227], v[42:45]
	v_mfma_f32_16x16x32_bf16 v[30:33], v[118:121], v[232:235], v[30:33]
	v_mfma_f32_16x16x32_bf16 v[26:29], v[126:129], v[232:235], v[26:29]
	v_mfma_f32_16x16x32_bf16 v[14:17], v[118:121], v[240:243], v[14:17]
	v_mfma_f32_16x16x32_bf16 v[10:13], v[126:129], v[240:243], v[10:13]
	s_setprio 0
	s_setprio 1
	v_mfma_f32_16x16x32_bf16 v[54:57], v[172:175], v[212:215], 0
	v_mfma_f32_16x16x32_bf16 v[50:53], v[180:183], v[212:215], 0
	v_mfma_f32_16x16x32_bf16 v[38:41], v[172:175], v[220:223], 0
	v_mfma_f32_16x16x32_bf16 v[34:37], v[180:183], v[220:223], 0
	v_mfma_f32_16x16x32_bf16 v[22:25], v[172:175], v[228:231], 0
	v_mfma_f32_16x16x32_bf16 v[18:21], v[180:183], v[228:231], 0
	v_mfma_f32_16x16x32_bf16 v[6:9], v[172:175], v[236:239], 0
	v_mfma_f32_16x16x32_bf16 v[2:5], v[180:183], v[236:239], 0
	v_mfma_f32_16x16x32_bf16 v[54:57], v[176:179], v[216:219], v[54:57]
	v_mfma_f32_16x16x32_bf16 v[50:53], v[190:193], v[216:219], v[50:53]
	v_mfma_f32_16x16x32_bf16 v[38:41], v[176:179], v[224:227], v[38:41]
	v_mfma_f32_16x16x32_bf16 v[34:37], v[190:193], v[224:227], v[34:37]
	v_mfma_f32_16x16x32_bf16 v[22:25], v[176:179], v[232:235], v[22:25]
	v_mfma_f32_16x16x32_bf16 v[18:21], v[190:193], v[232:235], v[18:21]
	v_mfma_f32_16x16x32_bf16 v[6:9], v[176:179], v[240:243], v[6:9]
	v_mfma_f32_16x16x32_bf16 v[2:5], v[190:193], v[240:243], v[2:5]
	s_setprio 0
	s_barrier
	s_add_i32 s89, 0, 0x18000
	s_add_i32 s90, 0, 0x1c000
	v_add_u32_e32 v126, s89, v185
	v_add_u32_e32 v189, s90, v185
	ds_read_b128 v[114:117], v126
	ds_read_b128 v[118:121], v126 offset:1024
	ds_read_b128 v[122:125], v126 offset:2048
	ds_read_b128 v[126:129], v126 offset:3072
	ds_read_b128 v[172:175], v189
	ds_read_b128 v[176:179], v189 offset:1024
	ds_read_b128 v[180:183], v189 offset:2048
	ds_read_b128 v[190:193], v189 offset:3072
	s_add_u32 s62, s62, 0x40000
	s_addc_u32 s63, s63, 0
	s_mov_b32 m0, s77
	v_lshl_add_u64 v[248:249], s[62:63], 0, v[0:1]
	ds_read_b128 v[212:215], v188 offset:32768
	ds_read_b128 v[216:219], v188 offset:33792
	ds_read_b128 v[220:223], v188 offset:34816
	ds_read_b128 v[224:227], v188 offset:35840
	ds_read_b128 v[228:231], v188 offset:36864
	ds_read_b128 v[232:235], v188 offset:37888
	ds_read_b128 v[236:239], v188 offset:38912
	ds_read_b128 v[240:243], v188 offset:39936
	global_load_lds_dwordx4 v[248:249], off
	v_lshl_add_u64 v[248:249], s[62:63], 0, v[164:165]
	s_mov_b32 m0, s78
	s_nop 0
	global_load_lds_dwordx4 v[248:249], off
	s_waitcnt vmcnt(8)
	s_waitcnt lgkmcnt(0)
	s_barrier
	s_setprio 1
	s_waitcnt lgkmcnt(0)
	v_mfma_f32_16x16x32_bf16 v[142:145], v[114:117], v[212:215], v[142:145]
	v_mfma_f32_16x16x32_bf16 v[138:141], v[122:125], v[212:215], v[138:141]
	v_mfma_f32_16x16x32_bf16 v[110:113], v[114:117], v[220:223], v[110:113]
	v_mfma_f32_16x16x32_bf16 v[106:109], v[122:125], v[220:223], v[106:109]
	v_mfma_f32_16x16x32_bf16 v[94:97], v[114:117], v[228:231], v[94:97]
	v_mfma_f32_16x16x32_bf16 v[90:93], v[122:125], v[228:231], v[90:93]
	v_mfma_f32_16x16x32_bf16 v[78:81], v[114:117], v[236:239], v[78:81]
	v_mfma_f32_16x16x32_bf16 v[74:77], v[122:125], v[236:239], v[74:77]
	v_mfma_f32_16x16x32_bf16 v[142:145], v[118:121], v[216:219], v[142:145]
	v_mfma_f32_16x16x32_bf16 v[138:141], v[126:129], v[216:219], v[138:141]
	v_mfma_f32_16x16x32_bf16 v[110:113], v[118:121], v[224:227], v[110:113]
	v_mfma_f32_16x16x32_bf16 v[106:109], v[126:129], v[224:227], v[106:109]
	v_mfma_f32_16x16x32_bf16 v[94:97], v[118:121], v[232:235], v[94:97]
	v_mfma_f32_16x16x32_bf16 v[90:93], v[126:129], v[232:235], v[90:93]
	v_mfma_f32_16x16x32_bf16 v[78:81], v[118:121], v[240:243], v[78:81]
	v_mfma_f32_16x16x32_bf16 v[74:77], v[126:129], v[240:243], v[74:77]
	s_setprio 0
	s_setprio 1
	v_mfma_f32_16x16x32_bf16 v[134:137], v[172:175], v[212:215], v[134:137]
	v_mfma_f32_16x16x32_bf16 v[130:133], v[180:183], v[212:215], v[130:133]
	v_mfma_f32_16x16x32_bf16 v[102:105], v[172:175], v[220:223], v[102:105]
	v_mfma_f32_16x16x32_bf16 v[98:101], v[180:183], v[220:223], v[98:101]
	v_mfma_f32_16x16x32_bf16 v[86:89], v[172:175], v[228:231], v[86:89]
	v_mfma_f32_16x16x32_bf16 v[82:85], v[180:183], v[228:231], v[82:85]
	v_mfma_f32_16x16x32_bf16 v[70:73], v[172:175], v[236:239], v[70:73]
	v_mfma_f32_16x16x32_bf16 v[66:69], v[180:183], v[236:239], v[66:69]
	v_mfma_f32_16x16x32_bf16 v[134:137], v[176:179], v[216:219], v[134:137]
	v_mfma_f32_16x16x32_bf16 v[130:133], v[190:193], v[216:219], v[130:133]
	v_mfma_f32_16x16x32_bf16 v[102:105], v[176:179], v[224:227], v[102:105]
	v_mfma_f32_16x16x32_bf16 v[98:101], v[190:193], v[224:227], v[98:101]
	v_mfma_f32_16x16x32_bf16 v[86:89], v[176:179], v[232:235], v[86:89]
	v_mfma_f32_16x16x32_bf16 v[82:85], v[190:193], v[232:235], v[82:85]
	v_mfma_f32_16x16x32_bf16 v[70:73], v[176:179], v[240:243], v[70:73]
	v_mfma_f32_16x16x32_bf16 v[66:69], v[190:193], v[240:243], v[66:69]
	s_setprio 0
	s_barrier
	s_add_i32 s62, s89, s65
	v_lshl_add_u64 v[148:149], v[148:149], 0, s[54:55]
	s_mov_b32 m0, s62
	ds_read_b128 v[212:215], v188 offset:49152
	ds_read_b128 v[216:219], v188 offset:50176
	ds_read_b128 v[220:223], v188 offset:51200
	ds_read_b128 v[224:227], v188 offset:52224
	ds_read_b128 v[228:231], v188 offset:53248
	ds_read_b128 v[232:235], v188 offset:54272
	ds_read_b128 v[236:239], v188 offset:55296
	ds_read_b128 v[240:243], v188 offset:56320
	global_load_lds_dwordx4 v[148:149], off
	s_add_i32 m0, s62, 0x2000
	s_add_u32 s60, s60, 0x40080
	v_lshl_add_u64 v[148:149], v[194:195], 0, s[54:55]
	s_addc_u32 s61, s61, 0
	s_add_i32 s62, s90, s65
	global_load_lds_dwordx4 v[148:149], off
	v_lshl_add_u64 v[148:149], s[60:61], 0, v[166:167]
	s_mov_b32 m0, s62
	s_nop 0
	global_load_lds_dwordx4 v[148:149], off
	v_lshl_add_u64 v[148:149], s[60:61], 0, v[162:163]
	s_add_i32 m0, s62, 0x2000
	s_nop 0
	global_load_lds_dwordx4 v[148:149], off
	v_lshl_add_u64 v[148:149], v[244:245], 0, s[54:55]
	s_mov_b32 m0, s79
	s_nop 0
	global_load_lds_dwordx4 v[148:149], off
	v_lshl_add_u64 v[148:149], v[246:247], 0, s[54:55]
	s_mov_b32 m0, s80
	s_nop 0
	global_load_lds_dwordx4 v[148:149], off
	s_waitcnt vmcnt(8)
	s_waitcnt lgkmcnt(0)
	s_barrier
	s_setprio 1
	s_waitcnt lgkmcnt(0)
	v_mfma_f32_16x16x32_bf16 v[62:65], v[114:117], v[212:215], v[62:65]
	v_mfma_f32_16x16x32_bf16 v[58:61], v[122:125], v[212:215], v[58:61]
	v_mfma_f32_16x16x32_bf16 v[46:49], v[114:117], v[220:223], v[46:49]
	v_mfma_f32_16x16x32_bf16 v[42:45], v[122:125], v[220:223], v[42:45]
	v_mfma_f32_16x16x32_bf16 v[30:33], v[114:117], v[228:231], v[30:33]
	v_mfma_f32_16x16x32_bf16 v[26:29], v[122:125], v[228:231], v[26:29]
	v_mfma_f32_16x16x32_bf16 v[14:17], v[114:117], v[236:239], v[14:17]
	v_mfma_f32_16x16x32_bf16 v[10:13], v[122:125], v[236:239], v[10:13]
	v_mfma_f32_16x16x32_bf16 v[62:65], v[118:121], v[216:219], v[62:65]
	v_mfma_f32_16x16x32_bf16 v[58:61], v[126:129], v[216:219], v[58:61]
	v_mfma_f32_16x16x32_bf16 v[46:49], v[118:121], v[224:227], v[46:49]
	v_mfma_f32_16x16x32_bf16 v[42:45], v[126:129], v[224:227], v[42:45]
	v_mfma_f32_16x16x32_bf16 v[30:33], v[118:121], v[232:235], v[30:33]
	v_mfma_f32_16x16x32_bf16 v[26:29], v[126:129], v[232:235], v[26:29]
	v_mfma_f32_16x16x32_bf16 v[14:17], v[118:121], v[240:243], v[14:17]
	v_mfma_f32_16x16x32_bf16 v[10:13], v[126:129], v[240:243], v[10:13]
	s_setprio 0
	s_setprio 1
	v_mfma_f32_16x16x32_bf16 v[54:57], v[172:175], v[212:215], v[54:57]
	v_mfma_f32_16x16x32_bf16 v[50:53], v[180:183], v[212:215], v[50:53]
	v_mfma_f32_16x16x32_bf16 v[38:41], v[172:175], v[220:223], v[38:41]
	v_mfma_f32_16x16x32_bf16 v[34:37], v[180:183], v[220:223], v[34:37]
	v_mfma_f32_16x16x32_bf16 v[22:25], v[172:175], v[228:231], v[22:25]
	v_mfma_f32_16x16x32_bf16 v[18:21], v[180:183], v[228:231], v[18:21]
	v_mfma_f32_16x16x32_bf16 v[6:9], v[172:175], v[236:239], v[6:9]
	v_mfma_f32_16x16x32_bf16 v[2:5], v[180:183], v[236:239], v[2:5]
	v_mfma_f32_16x16x32_bf16 v[54:57], v[176:179], v[216:219], v[54:57]
	v_mfma_f32_16x16x32_bf16 v[50:53], v[190:193], v[216:219], v[50:53]
	v_mfma_f32_16x16x32_bf16 v[38:41], v[176:179], v[224:227], v[38:41]
	v_mfma_f32_16x16x32_bf16 v[34:37], v[190:193], v[224:227], v[34:37]
	v_mfma_f32_16x16x32_bf16 v[22:25], v[176:179], v[232:235], v[22:25]
	v_mfma_f32_16x16x32_bf16 v[18:21], v[190:193], v[232:235], v[18:21]
	v_mfma_f32_16x16x32_bf16 v[6:9], v[176:179], v[240:243], v[6:9]
	v_mfma_f32_16x16x32_bf16 v[2:5], v[190:193], v[240:243], v[2:5]
	s_setprio 0
	s_barrier
	s_add_u32 s58, s58, 0x100
	s_addc_u32 s59, s59, 0
	s_add_u32 s86, s86, 0x100
	s_addc_u32 s87, s87, 0
	s_cmp_ge_i32 s88, s64
	s_mov_b32 s60, s88
	s_cbranch_scc0 .LBB0_530
	s_branch .Lpeel_p3a_after

.Lpeel_p3a_after:
	s_and_b64 vcc, exec, s[40:41]
	s_cbranch_vccz .LBB0_533
